# conv item top: the weight loads are issued before the workgroup barrier instead of after it
# speedup vs baseline: 1.0021x; 1.0021x over previous
.LBB0_555:
	v_lshrrev_b32_e32 v3, 12, v226
	v_cmp_gt_i32_e32 vcc, s10, v1
	v_lshrrev_b32_e32 v2, 4, v1
	v_add_u32_e32 v3, 32, v3
	v_cndmask_b32_e32 v2, v3, v2, vcc
	v_lshlrev_b32_e32 v2, 5, v2
	v_add3_u32 v2, v226, v2, s11
	v_ashrrev_i32_e32 v3, 31, v2
	v_lshlrev_b64 v[136:137], 10, v[2:3]
	v_lshl_add_u64 v[148:149], v[78:79], 0, v[136:137]
	s_nop 0
	s_nop 0
	global_load_dwordx2 v[134:135], v[18:19], off
	global_load_dwordx2 v[132:133], v[18:19], off offset:2048
	global_load_dwordx2 v[130:131], v[20:21], off
	global_load_dwordx2 v[128:129], v[22:23], off
	global_load_dwordx2 v[2:3], v[24:25], off
	global_load_dwordx2 v[4:5], v[26:27], off
	global_load_dwordx2 v[6:7], v[28:29], off
	global_load_dwordx2 v[8:9], v[30:31], off
	global_load_dwordx2 v[10:11], v[32:33], off
	global_load_dwordx2 v[12:13], v[34:35], off
	global_load_dwordx2 v[14:15], v[36:37], off
	global_load_dwordx2 v[16:17], v[38:39], off
	global_load_dwordx2 v[90:91], v[40:41], off
	global_load_dwordx2 v[92:93], v[42:43], off
	global_load_dwordx2 v[94:95], v[44:45], off
	global_load_dwordx2 v[96:97], v[46:47], off
	global_load_dwordx2 v[98:99], v[48:49], off
	global_load_dwordx2 v[100:101], v[50:51], off
	global_load_dwordx2 v[102:103], v[52:53], off
	global_load_dwordx2 v[104:105], v[54:55], off
	global_load_dwordx2 v[106:107], v[56:57], off
	global_load_dwordx2 v[108:109], v[58:59], off
	global_load_dwordx2 v[110:111], v[60:61], off
	global_load_dwordx2 v[112:113], v[62:63], off
	global_load_dwordx2 v[114:115], v[64:65], off
	global_load_dwordx2 v[116:117], v[66:67], off
	global_load_dwordx2 v[118:119], v[68:69], off
	global_load_dwordx2 v[120:121], v[70:71], off
	global_load_dwordx2 v[122:123], v[72:73], off
	global_load_dwordx2 v[124:125], v[74:75], off
	global_load_dwordx2 v[126:127], v[76:77], off
	global_load_dwordx2 v[136:137], v[80:81], off
	s_waitcnt lgkmcnt(0)
	s_barrier
	s_waitcnt vmcnt(32)
	v_mov_b32_e32 v138, v246
	v_mov_b32_e32 v139, v247
	v_mov_b32_e32 v140, v248
	v_mov_b32_e32 v141, v249
	v_mov_b32_e32 v142, v250
	v_mov_b32_e32 v143, v251
	v_add_u32_e32 v1, s8, v1
	s_nop 0
	v_lshlrev_b32_e32 v178, 16, v156
	s_nop 0
	v_lshlrev_b32_e32 v170, 16, v152
	s_nop 0
	v_and_b32_e32 v171, 0xffff0000, v152
	s_nop 0
	v_and_b32_e32 v179, 0xffff0000, v156
	s_nop 0
	v_lshlrev_b32_e32 v186, 16, v158
	v_and_b32_e32 v187, 0xffff0000, v158
	s_nop 0
	v_lshlrev_b32_e32 v162, 16, v150
	s_nop 0
	v_lshlrev_b32_e32 v154, 16, v145
	v_and_b32_e32 v155, 0xffff0000, v145
	v_and_b32_e32 v163, 0xffff0000, v150
	v_lshlrev_b32_e32 v196, 16, v160
	v_and_b32_e32 v197, 0xffff0000, v160
	v_lshlrev_b32_e32 v198, 16, v164
	v_and_b32_e32 v199, 0xffff0000, v164
	v_lshlrev_b32_e32 v150, 16, v151
	v_and_b32_e32 v151, 0xffff0000, v151
	v_lshlrev_b32_e32 v152, 16, v153
	v_and_b32_e32 v153, 0xffff0000, v153
	v_lshlrev_b32_e32 v156, 16, v157
	v_and_b32_e32 v157, 0xffff0000, v157
	v_lshlrev_b32_e32 v158, 16, v159
	v_and_b32_e32 v159, 0xffff0000, v159
	v_lshlrev_b32_e32 v160, 16, v161
	v_and_b32_e32 v161, 0xffff0000, v161
	v_lshlrev_b32_e32 v164, 16, v165
	v_and_b32_e32 v165, 0xffff0000, v165
	v_lshlrev_b32_e32 v180, 16, v181
	v_and_b32_e32 v181, 0xffff0000, v181
	v_lshlrev_b32_e32 v182, 16, v183
	v_and_b32_e32 v183, 0xffff0000, v183
	v_lshlrev_b32_e32 v184, 16, v185
	v_and_b32_e32 v185, 0xffff0000, v185
	v_lshlrev_b32_e32 v188, 16, v189
	v_and_b32_e32 v189, 0xffff0000, v189
	v_lshlrev_b32_e32 v190, 16, v191
	v_and_b32_e32 v191, 0xffff0000, v191
	v_lshlrev_b32_e32 v192, 16, v193
	v_and_b32_e32 v193, 0xffff0000, v193
	v_lshlrev_b32_e32 v194, 16, v195
	v_and_b32_e32 v195, 0xffff0000, v195
	v_lshlrev_b32_e32 v200, 16, v201
	v_and_b32_e32 v201, 0xffff0000, v201
	v_lshlrev_b32_e32 v202, 16, v203
	v_and_b32_e32 v203, 0xffff0000, v203
	v_lshlrev_b32_e32 v204, 16, v205
	v_and_b32_e32 v205, 0xffff0000, v205
	s_waitcnt vmcnt(0)
	v_lshlrev_b32_e32 v148, 16, v146
	v_and_b32_e32 v149, 0xffff0000, v146
	v_pk_fma_f32 v[148:149], v[148:149], v[134:135], v[136:137]
	v_lshlrev_b32_e32 v146, 16, v147
	v_pk_fma_f32 v[148:149], v[154:155], v[132:133], v[148:149]
	v_pk_fma_f32 v[154:155], v[154:155], v[134:135], v[136:137]
	v_pk_fma_f32 v[148:149], v[162:163], v[130:131], v[148:149]
	v_pk_fma_f32 v[154:155], v[162:163], v[132:133], v[154:155]
	v_pk_fma_f32 v[162:163], v[162:163], v[134:135], v[136:137]
	v_pk_fma_f32 v[148:149], v[170:171], v[128:129], v[148:149]
	v_pk_fma_f32 v[154:155], v[170:171], v[130:131], v[154:155]
	v_pk_fma_f32 v[162:163], v[170:171], v[132:133], v[162:163]
	v_pk_fma_f32 v[170:171], v[170:171], v[134:135], v[136:137]
	v_pk_fma_f32 v[148:149], v[178:179], v[2:3], v[148:149]
	v_pk_fma_f32 v[154:155], v[178:179], v[128:129], v[154:155]
	v_pk_fma_f32 v[162:163], v[178:179], v[130:131], v[162:163]
	v_pk_fma_f32 v[170:171], v[178:179], v[132:133], v[170:171]
	v_pk_fma_f32 v[178:179], v[178:179], v[134:135], v[136:137]
	v_pk_fma_f32 v[148:149], v[186:187], v[4:5], v[148:149]
	v_pk_fma_f32 v[154:155], v[186:187], v[2:3], v[154:155]
	v_pk_fma_f32 v[162:163], v[186:187], v[128:129], v[162:163]
	v_pk_fma_f32 v[170:171], v[186:187], v[130:131], v[170:171]
	v_pk_fma_f32 v[178:179], v[186:187], v[132:133], v[178:179]
	v_pk_fma_f32 v[186:187], v[186:187], v[134:135], v[136:137]
	v_pk_fma_f32 v[148:149], v[196:197], v[6:7], v[148:149]
	v_pk_fma_f32 v[154:155], v[196:197], v[4:5], v[154:155]
	v_pk_fma_f32 v[162:163], v[196:197], v[2:3], v[162:163]
	v_pk_fma_f32 v[170:171], v[196:197], v[128:129], v[170:171]
	v_pk_fma_f32 v[178:179], v[196:197], v[130:131], v[178:179]
	v_pk_fma_f32 v[186:187], v[196:197], v[132:133], v[186:187]
	v_pk_fma_f32 v[196:197], v[196:197], v[134:135], v[136:137]
	v_pk_fma_f32 v[148:149], v[198:199], v[8:9], v[148:149]
	v_pk_fma_f32 v[154:155], v[198:199], v[6:7], v[154:155]
	v_pk_fma_f32 v[162:163], v[198:199], v[4:5], v[162:163]
	v_pk_fma_f32 v[170:171], v[198:199], v[2:3], v[170:171]
	v_pk_fma_f32 v[178:179], v[198:199], v[128:129], v[178:179]
	v_pk_fma_f32 v[186:187], v[198:199], v[130:131], v[186:187]
	v_pk_fma_f32 v[228:229], v[198:199], v[132:133], v[196:197]
	v_pk_fma_f32 v[198:199], v[198:199], v[134:135], v[136:137]
	v_lshlrev_b32_e32 v196, 16, v166
	v_and_b32_e32 v197, 0xffff0000, v166
	v_pk_fma_f32 v[148:149], v[196:197], v[10:11], v[148:149]
	v_pk_fma_f32 v[154:155], v[196:197], v[8:9], v[154:155]
	v_pk_fma_f32 v[162:163], v[196:197], v[6:7], v[162:163]
	v_pk_fma_f32 v[170:171], v[196:197], v[4:5], v[170:171]
	v_pk_fma_f32 v[178:179], v[196:197], v[2:3], v[178:179]
	v_pk_fma_f32 v[186:187], v[196:197], v[128:129], v[186:187]
	v_pk_fma_f32 v[230:231], v[196:197], v[132:133], v[198:199]
	v_lshlrev_b32_e32 v198, 16, v168
	v_and_b32_e32 v199, 0xffff0000, v168
	v_pk_fma_f32 v[228:229], v[196:197], v[130:131], v[228:229]
	v_pk_fma_f32 v[148:149], v[198:199], v[12:13], v[148:149]
	v_pk_fma_f32 v[154:155], v[198:199], v[10:11], v[154:155]
	v_pk_fma_f32 v[162:163], v[198:199], v[8:9], v[162:163]
	v_pk_fma_f32 v[170:171], v[198:199], v[6:7], v[170:171]
	v_pk_fma_f32 v[178:179], v[198:199], v[4:5], v[178:179]
	v_pk_fma_f32 v[232:233], v[198:199], v[2:3], v[186:187]
	v_lshlrev_b32_e32 v186, 16, v172
	v_and_b32_e32 v187, 0xffff0000, v172
	v_pk_fma_f32 v[196:197], v[196:197], v[134:135], v[136:137]
	v_pk_fma_f32 v[228:229], v[198:199], v[128:129], v[228:229]
	v_pk_fma_f32 v[230:231], v[198:199], v[130:131], v[230:231]
	v_pk_fma_f32 v[148:149], v[186:187], v[14:15], v[148:149]
	v_pk_fma_f32 v[154:155], v[186:187], v[12:13], v[154:155]
	v_pk_fma_f32 v[162:163], v[186:187], v[10:11], v[162:163]
	v_pk_fma_f32 v[170:171], v[186:187], v[8:9], v[170:171]
	v_pk_fma_f32 v[234:235], v[186:187], v[6:7], v[178:179]
	v_lshlrev_b32_e32 v178, 16, v174
	v_and_b32_e32 v179, 0xffff0000, v174
	v_pk_fma_f32 v[196:197], v[198:199], v[132:133], v[196:197]
	v_pk_fma_f32 v[198:199], v[198:199], v[134:135], v[136:137]
	v_pk_fma_f32 v[232:233], v[186:187], v[4:5], v[232:233]
	v_pk_fma_f32 v[228:229], v[186:187], v[2:3], v[228:229]
	v_pk_fma_f32 v[230:231], v[186:187], v[128:129], v[230:231]
	v_pk_fma_f32 v[148:149], v[178:179], v[16:17], v[148:149]
	v_pk_fma_f32 v[154:155], v[178:179], v[14:15], v[154:155]
	v_pk_fma_f32 v[162:163], v[178:179], v[12:13], v[162:163]
	v_pk_fma_f32 v[236:237], v[178:179], v[10:11], v[170:171]
	v_lshlrev_b32_e32 v170, 16, v176
	v_and_b32_e32 v171, 0xffff0000, v176
	v_pk_fma_f32 v[196:197], v[186:187], v[130:131], v[196:197]
	v_pk_fma_f32 v[198:199], v[186:187], v[132:133], v[198:199]
	v_pk_fma_f32 v[186:187], v[186:187], v[134:135], v[136:137]
	v_pk_fma_f32 v[234:235], v[178:179], v[8:9], v[234:235]
	v_pk_fma_f32 v[232:233], v[178:179], v[6:7], v[232:233]
	v_pk_fma_f32 v[228:229], v[178:179], v[4:5], v[228:229]
	v_pk_fma_f32 v[230:231], v[178:179], v[2:3], v[230:231]
	v_pk_fma_f32 v[148:149], v[170:171], v[90:91], v[148:149]
	v_pk_fma_f32 v[154:155], v[170:171], v[16:17], v[154:155]
	v_pk_fma_f32 v[238:239], v[170:171], v[14:15], v[162:163]
	v_lshlrev_b32_e32 v162, 16, v144
	v_and_b32_e32 v163, 0xffff0000, v144
	v_pk_fma_f32 v[196:197], v[178:179], v[128:129], v[196:197]
	v_pk_fma_f32 v[198:199], v[178:179], v[130:131], v[198:199]
	v_pk_fma_f32 v[186:187], v[178:179], v[132:133], v[186:187]
	v_pk_fma_f32 v[178:179], v[178:179], v[134:135], v[136:137]
	v_pk_fma_f32 v[236:237], v[170:171], v[12:13], v[236:237]
	v_pk_fma_f32 v[234:235], v[170:171], v[10:11], v[234:235]
	v_pk_fma_f32 v[232:233], v[170:171], v[8:9], v[232:233]
	v_pk_fma_f32 v[228:229], v[170:171], v[6:7], v[228:229]
	v_pk_fma_f32 v[230:231], v[170:171], v[4:5], v[230:231]
	v_pk_fma_f32 v[144:145], v[162:163], v[92:93], v[148:149]
	v_pk_fma_f32 v[148:149], v[162:163], v[90:91], v[154:155]
	v_lshlrev_b32_e32 v154, 16, v143
	v_and_b32_e32 v155, 0xffff0000, v143
	v_pk_fma_f32 v[196:197], v[170:171], v[2:3], v[196:197]
	v_pk_fma_f32 v[198:199], v[170:171], v[128:129], v[198:199]
	v_pk_fma_f32 v[186:187], v[170:171], v[130:131], v[186:187]
	v_pk_fma_f32 v[178:179], v[170:171], v[132:133], v[178:179]
	v_pk_fma_f32 v[170:171], v[170:171], v[134:135], v[136:137]
	v_pk_fma_f32 v[238:239], v[162:163], v[16:17], v[238:239]
	v_pk_fma_f32 v[236:237], v[162:163], v[14:15], v[236:237]
	v_pk_fma_f32 v[234:235], v[162:163], v[12:13], v[234:235]
	v_pk_fma_f32 v[232:233], v[162:163], v[10:11], v[232:233]
	v_pk_fma_f32 v[228:229], v[162:163], v[8:9], v[228:229]
	v_pk_fma_f32 v[230:231], v[162:163], v[6:7], v[230:231]
	v_pk_fma_f32 v[144:145], v[154:155], v[94:95], v[144:145]
	v_pk_fma_f32 v[240:241], v[154:155], v[92:93], v[148:149]
	v_lshlrev_b32_e32 v148, 16, v142
	v_and_b32_e32 v149, 0xffff0000, v142
	v_pk_fma_f32 v[196:197], v[162:163], v[4:5], v[196:197]
	v_pk_fma_f32 v[198:199], v[162:163], v[2:3], v[198:199]
	v_pk_fma_f32 v[186:187], v[162:163], v[128:129], v[186:187]
	v_pk_fma_f32 v[178:179], v[162:163], v[130:131], v[178:179]
	v_pk_fma_f32 v[170:171], v[162:163], v[132:133], v[170:171]
	v_pk_fma_f32 v[162:163], v[162:163], v[134:135], v[136:137]
	v_pk_fma_f32 v[238:239], v[154:155], v[90:91], v[238:239]
	v_pk_fma_f32 v[236:237], v[154:155], v[16:17], v[236:237]
	v_pk_fma_f32 v[234:235], v[154:155], v[14:15], v[234:235]
	v_pk_fma_f32 v[232:233], v[154:155], v[12:13], v[232:233]
	v_pk_fma_f32 v[228:229], v[154:155], v[10:11], v[228:229]
	v_pk_fma_f32 v[230:231], v[154:155], v[8:9], v[230:231]
	v_pk_fma_f32 v[142:143], v[148:149], v[96:97], v[144:145]
	v_lshlrev_b32_e32 v144, 16, v141
	v_and_b32_e32 v145, 0xffff0000, v141
	v_pk_fma_f32 v[196:197], v[154:155], v[6:7], v[196:197]
	v_pk_fma_f32 v[198:199], v[154:155], v[4:5], v[198:199]
	v_pk_fma_f32 v[186:187], v[154:155], v[2:3], v[186:187]
	v_pk_fma_f32 v[178:179], v[154:155], v[128:129], v[178:179]
	v_pk_fma_f32 v[170:171], v[154:155], v[130:131], v[170:171]
	v_pk_fma_f32 v[162:163], v[154:155], v[132:133], v[162:163]
	v_pk_fma_f32 v[154:155], v[154:155], v[134:135], v[136:137]
	v_pk_fma_f32 v[134:135], v[148:149], v[134:135], v[136:137]
	v_pk_fma_f32 v[242:243], v[144:145], v[98:99], v[142:143]
	v_lshlrev_b32_e32 v142, 16, v140
	v_and_b32_e32 v143, 0xffff0000, v140
	v_pk_fma_f32 v[154:155], v[148:149], v[132:133], v[154:155]
	v_pk_fma_f32 v[132:133], v[144:145], v[132:133], v[134:135]
	v_lshlrev_b32_e32 v140, 16, v138
	v_and_b32_e32 v141, 0xffff0000, v138
	v_pk_fma_f32 v[162:163], v[148:149], v[130:131], v[162:163]
	v_pk_fma_f32 v[154:155], v[144:145], v[130:131], v[154:155]
	v_pk_fma_f32 v[130:131], v[142:143], v[130:131], v[132:133]
	v_lshlrev_b32_e32 v138, 16, v139
	v_and_b32_e32 v139, 0xffff0000, v139
	v_pk_fma_f32 v[170:171], v[148:149], v[128:129], v[170:171]
	v_pk_fma_f32 v[162:163], v[144:145], v[128:129], v[162:163]
	v_pk_fma_f32 v[154:155], v[142:143], v[128:129], v[154:155]
	v_pk_fma_f32 v[128:129], v[140:141], v[128:129], v[130:131]
	v_and_b32_e32 v147, 0xffff0000, v147
	v_pk_fma_f32 v[178:179], v[148:149], v[2:3], v[178:179]
	v_pk_fma_f32 v[170:171], v[144:145], v[2:3], v[170:171]
	v_pk_fma_f32 v[162:163], v[142:143], v[2:3], v[162:163]
	v_pk_fma_f32 v[154:155], v[140:141], v[2:3], v[154:155]
	v_pk_fma_f32 v[2:3], v[138:139], v[2:3], v[128:129]
	v_pk_fma_f32 v[198:199], v[148:149], v[6:7], v[198:199]
	v_pk_fma_f32 v[2:3], v[146:147], v[4:5], v[2:3]
	v_pk_fma_f32 v[186:187], v[148:149], v[4:5], v[186:187]
	v_pk_fma_f32 v[178:179], v[144:145], v[4:5], v[178:179]
	v_pk_fma_f32 v[170:171], v[142:143], v[4:5], v[170:171]
	v_pk_fma_f32 v[162:163], v[140:141], v[4:5], v[162:163]
	v_pk_fma_f32 v[154:155], v[138:139], v[4:5], v[154:155]
	v_pk_fma_f32 v[2:3], v[150:151], v[6:7], v[2:3]
	v_pk_fma_f32 v[228:229], v[148:149], v[12:13], v[228:229]
	v_pk_fma_f32 v[230:231], v[148:149], v[10:11], v[230:231]
	v_pk_fma_f32 v[196:197], v[148:149], v[8:9], v[196:197]
	v_pk_fma_f32 v[198:199], v[144:145], v[8:9], v[198:199]
	v_pk_fma_f32 v[186:187], v[144:145], v[6:7], v[186:187]
	v_pk_fma_f32 v[178:179], v[142:143], v[6:7], v[178:179]
	v_pk_fma_f32 v[170:171], v[140:141], v[6:7], v[170:171]
	v_pk_fma_f32 v[162:163], v[138:139], v[6:7], v[162:163]
	v_pk_fma_f32 v[154:155], v[146:147], v[6:7], v[154:155]
	v_pk_fma_f32 v[2:3], v[152:153], v[8:9], v[2:3]
	v_pk_fma_f32 v[228:229], v[144:145], v[14:15], v[228:229]
	v_pk_fma_f32 v[230:231], v[144:145], v[12:13], v[230:231]
	v_pk_fma_f32 v[196:197], v[144:145], v[10:11], v[196:197]
	v_pk_fma_f32 v[198:199], v[142:143], v[10:11], v[198:199]
	v_pk_fma_f32 v[186:187], v[142:143], v[8:9], v[186:187]
	v_pk_fma_f32 v[178:179], v[140:141], v[8:9], v[178:179]
	v_pk_fma_f32 v[170:171], v[138:139], v[8:9], v[170:171]
	v_pk_fma_f32 v[162:163], v[146:147], v[8:9], v[162:163]
	v_pk_fma_f32 v[154:155], v[150:151], v[8:9], v[154:155]
	v_pk_fma_f32 v[2:3], v[156:157], v[10:11], v[2:3]
	v_pk_fma_f32 v[232:233], v[148:149], v[14:15], v[232:233]
	v_pk_fma_f32 v[228:229], v[142:143], v[16:17], v[228:229]
	v_pk_fma_f32 v[230:231], v[142:143], v[14:15], v[230:231]
	v_pk_fma_f32 v[196:197], v[142:143], v[12:13], v[196:197]
	v_pk_fma_f32 v[198:199], v[140:141], v[12:13], v[198:199]
	v_pk_fma_f32 v[186:187], v[140:141], v[10:11], v[186:187]
	v_pk_fma_f32 v[178:179], v[138:139], v[10:11], v[178:179]
	v_pk_fma_f32 v[170:171], v[146:147], v[10:11], v[170:171]
	v_pk_fma_f32 v[162:163], v[150:151], v[10:11], v[162:163]
	v_pk_fma_f32 v[154:155], v[152:153], v[10:11], v[154:155]
	v_pk_fma_f32 v[2:3], v[158:159], v[12:13], v[2:3]
	v_pk_fma_f32 v[234:235], v[148:149], v[16:17], v[234:235]
	v_pk_fma_f32 v[232:233], v[144:145], v[16:17], v[232:233]
	v_pk_fma_f32 v[228:229], v[140:141], v[90:91], v[228:229]
	v_pk_fma_f32 v[230:231], v[140:141], v[16:17], v[230:231]
	v_pk_fma_f32 v[196:197], v[140:141], v[14:15], v[196:197]
	v_pk_fma_f32 v[198:199], v[138:139], v[14:15], v[198:199]
	v_pk_fma_f32 v[186:187], v[138:139], v[12:13], v[186:187]
	v_pk_fma_f32 v[178:179], v[146:147], v[12:13], v[178:179]
	v_pk_fma_f32 v[170:171], v[150:151], v[12:13], v[170:171]
	v_pk_fma_f32 v[162:163], v[152:153], v[12:13], v[162:163]
	v_pk_fma_f32 v[154:155], v[156:157], v[12:13], v[154:155]
	v_pk_fma_f32 v[2:3], v[160:161], v[14:15], v[2:3]
	v_pk_fma_f32 v[236:237], v[148:149], v[90:91], v[236:237]
	v_pk_fma_f32 v[234:235], v[144:145], v[90:91], v[234:235]
	v_pk_fma_f32 v[232:233], v[142:143], v[90:91], v[232:233]
	v_pk_fma_f32 v[228:229], v[138:139], v[92:93], v[228:229]
	v_pk_fma_f32 v[230:231], v[138:139], v[90:91], v[230:231]
	v_lshlrev_b32_e32 v166, 16, v167
	v_and_b32_e32 v167, 0xffff0000, v167
	v_pk_fma_f32 v[196:197], v[138:139], v[16:17], v[196:197]
	v_pk_fma_f32 v[198:199], v[146:147], v[16:17], v[198:199]
	v_pk_fma_f32 v[186:187], v[146:147], v[14:15], v[186:187]
	v_pk_fma_f32 v[178:179], v[150:151], v[14:15], v[178:179]
	v_pk_fma_f32 v[170:171], v[152:153], v[14:15], v[170:171]
	v_pk_fma_f32 v[162:163], v[156:157], v[14:15], v[162:163]
	v_pk_fma_f32 v[154:155], v[158:159], v[14:15], v[154:155]
	v_pk_fma_f32 v[2:3], v[164:165], v[16:17], v[2:3]
	v_pk_fma_f32 v[240:241], v[148:149], v[94:95], v[240:241]
	v_pk_fma_f32 v[238:239], v[148:149], v[92:93], v[238:239]
	v_pk_fma_f32 v[236:237], v[144:145], v[92:93], v[236:237]
	v_pk_fma_f32 v[234:235], v[142:143], v[92:93], v[234:235]
	v_pk_fma_f32 v[232:233], v[140:141], v[92:93], v[232:233]
	v_pk_fma_f32 v[228:229], v[146:147], v[94:95], v[228:229]
	v_pk_fma_f32 v[230:231], v[146:147], v[92:93], v[230:231]
	v_lshlrev_b32_e32 v168, 16, v169
	v_and_b32_e32 v169, 0xffff0000, v169
	v_pk_fma_f32 v[196:197], v[146:147], v[90:91], v[196:197]
	v_pk_fma_f32 v[198:199], v[150:151], v[90:91], v[198:199]
	v_pk_fma_f32 v[186:187], v[150:151], v[16:17], v[186:187]
	v_pk_fma_f32 v[178:179], v[152:153], v[16:17], v[178:179]
	v_pk_fma_f32 v[170:171], v[156:157], v[16:17], v[170:171]
	v_pk_fma_f32 v[162:163], v[158:159], v[16:17], v[162:163]
	v_pk_fma_f32 v[154:155], v[160:161], v[16:17], v[154:155]
	v_pk_fma_f32 v[2:3], v[166:167], v[90:91], v[2:3]
	v_pk_fma_f32 v[240:241], v[144:145], v[96:97], v[240:241]
	v_pk_fma_f32 v[238:239], v[144:145], v[94:95], v[238:239]
	v_pk_fma_f32 v[236:237], v[142:143], v[94:95], v[236:237]
	v_pk_fma_f32 v[234:235], v[140:141], v[94:95], v[234:235]
	v_pk_fma_f32 v[232:233], v[138:139], v[94:95], v[232:233]
	v_pk_fma_f32 v[228:229], v[150:151], v[96:97], v[228:229]
	v_pk_fma_f32 v[230:231], v[150:151], v[94:95], v[230:231]
	v_lshlrev_b32_e32 v172, 16, v173
	v_and_b32_e32 v173, 0xffff0000, v173
	v_pk_fma_f32 v[196:197], v[150:151], v[92:93], v[196:197]
	v_pk_fma_f32 v[198:199], v[152:153], v[92:93], v[198:199]
	v_pk_fma_f32 v[186:187], v[152:153], v[90:91], v[186:187]
	v_pk_fma_f32 v[178:179], v[156:157], v[90:91], v[178:179]
	v_pk_fma_f32 v[170:171], v[158:159], v[90:91], v[170:171]
	v_pk_fma_f32 v[162:163], v[160:161], v[90:91], v[162:163]
	v_pk_fma_f32 v[154:155], v[164:165], v[90:91], v[154:155]
	v_pk_fma_f32 v[2:3], v[168:169], v[92:93], v[2:3]
	v_pk_fma_f32 v[240:241], v[142:143], v[98:99], v[240:241]
	v_pk_fma_f32 v[238:239], v[142:143], v[96:97], v[238:239]
	v_pk_fma_f32 v[236:237], v[140:141], v[96:97], v[236:237]
	v_pk_fma_f32 v[234:235], v[138:139], v[96:97], v[234:235]
	v_pk_fma_f32 v[232:233], v[146:147], v[96:97], v[232:233]
	v_pk_fma_f32 v[228:229], v[152:153], v[98:99], v[228:229]
	v_pk_fma_f32 v[230:231], v[152:153], v[96:97], v[230:231]
	v_lshlrev_b32_e32 v174, 16, v175
	v_and_b32_e32 v175, 0xffff0000, v175
	v_pk_fma_f32 v[196:197], v[152:153], v[94:95], v[196:197]
	v_pk_fma_f32 v[198:199], v[156:157], v[94:95], v[198:199]
	v_pk_fma_f32 v[186:187], v[156:157], v[92:93], v[186:187]
	v_pk_fma_f32 v[178:179], v[158:159], v[92:93], v[178:179]
	v_pk_fma_f32 v[170:171], v[160:161], v[92:93], v[170:171]
	v_pk_fma_f32 v[162:163], v[164:165], v[92:93], v[162:163]
	v_pk_fma_f32 v[154:155], v[166:167], v[92:93], v[154:155]
	v_pk_fma_f32 v[2:3], v[172:173], v[94:95], v[2:3]
	v_pk_fma_f32 v[242:243], v[142:143], v[100:101], v[242:243]
	v_pk_fma_f32 v[240:241], v[140:141], v[100:101], v[240:241]
	v_pk_fma_f32 v[238:239], v[140:141], v[98:99], v[238:239]
	v_pk_fma_f32 v[236:237], v[138:139], v[98:99], v[236:237]
	v_pk_fma_f32 v[234:235], v[146:147], v[98:99], v[234:235]
	v_pk_fma_f32 v[232:233], v[150:151], v[98:99], v[232:233]
	v_pk_fma_f32 v[228:229], v[156:157], v[100:101], v[228:229]
	v_pk_fma_f32 v[230:231], v[156:157], v[98:99], v[230:231]
	v_lshlrev_b32_e32 v176, 16, v177
	v_and_b32_e32 v177, 0xffff0000, v177
	v_pk_fma_f32 v[196:197], v[156:157], v[96:97], v[196:197]
	v_pk_fma_f32 v[198:199], v[158:159], v[96:97], v[198:199]
	v_pk_fma_f32 v[186:187], v[158:159], v[94:95], v[186:187]
	v_pk_fma_f32 v[178:179], v[160:161], v[94:95], v[178:179]
	v_pk_fma_f32 v[170:171], v[164:165], v[94:95], v[170:171]
	v_pk_fma_f32 v[162:163], v[166:167], v[94:95], v[162:163]
	v_pk_fma_f32 v[154:155], v[168:169], v[94:95], v[154:155]
	v_pk_fma_f32 v[2:3], v[174:175], v[96:97], v[2:3]
	v_pk_fma_f32 v[242:243], v[140:141], v[102:103], v[242:243]
	v_pk_fma_f32 v[240:241], v[138:139], v[102:103], v[240:241]
	v_pk_fma_f32 v[238:239], v[138:139], v[100:101], v[238:239]
	v_pk_fma_f32 v[236:237], v[146:147], v[100:101], v[236:237]
	v_pk_fma_f32 v[234:235], v[150:151], v[100:101], v[234:235]
	v_pk_fma_f32 v[232:233], v[152:153], v[100:101], v[232:233]
	v_pk_fma_f32 v[228:229], v[158:159], v[102:103], v[228:229]
	v_pk_fma_f32 v[230:231], v[158:159], v[100:101], v[230:231]
	v_pk_fma_f32 v[196:197], v[158:159], v[98:99], v[196:197]
	v_pk_fma_f32 v[198:199], v[160:161], v[98:99], v[198:199]
	v_pk_fma_f32 v[186:187], v[160:161], v[96:97], v[186:187]
	v_pk_fma_f32 v[178:179], v[164:165], v[96:97], v[178:179]
	v_pk_fma_f32 v[170:171], v[166:167], v[96:97], v[170:171]
	v_pk_fma_f32 v[162:163], v[168:169], v[96:97], v[162:163]
	v_pk_fma_f32 v[154:155], v[172:173], v[96:97], v[154:155]
	v_pk_fma_f32 v[2:3], v[176:177], v[98:99], v[2:3]
	v_pk_fma_f32 v[242:243], v[138:139], v[104:105], v[242:243]
	v_pk_fma_f32 v[240:241], v[146:147], v[104:105], v[240:241]
	v_pk_fma_f32 v[238:239], v[146:147], v[102:103], v[238:239]
	v_pk_fma_f32 v[236:237], v[150:151], v[102:103], v[236:237]
	v_pk_fma_f32 v[234:235], v[152:153], v[102:103], v[234:235]
	v_pk_fma_f32 v[232:233], v[156:157], v[102:103], v[232:233]
	v_pk_fma_f32 v[228:229], v[160:161], v[104:105], v[228:229]
	v_pk_fma_f32 v[230:231], v[160:161], v[102:103], v[230:231]
	v_pk_fma_f32 v[196:197], v[160:161], v[100:101], v[196:197]
	v_pk_fma_f32 v[198:199], v[164:165], v[100:101], v[198:199]
	v_pk_fma_f32 v[186:187], v[164:165], v[98:99], v[186:187]
	v_pk_fma_f32 v[178:179], v[166:167], v[98:99], v[178:179]
	v_pk_fma_f32 v[170:171], v[168:169], v[98:99], v[170:171]
	v_pk_fma_f32 v[162:163], v[172:173], v[98:99], v[162:163]
	v_pk_fma_f32 v[154:155], v[174:175], v[98:99], v[154:155]
	v_pk_fma_f32 v[2:3], v[180:181], v[100:101], v[2:3]
	v_pk_fma_f32 v[242:243], v[146:147], v[106:107], v[242:243]
	v_pk_fma_f32 v[240:241], v[150:151], v[106:107], v[240:241]
	v_pk_fma_f32 v[238:239], v[150:151], v[104:105], v[238:239]
	v_pk_fma_f32 v[236:237], v[152:153], v[104:105], v[236:237]
	v_pk_fma_f32 v[234:235], v[156:157], v[104:105], v[234:235]
	v_pk_fma_f32 v[232:233], v[158:159], v[104:105], v[232:233]
	v_pk_fma_f32 v[228:229], v[164:165], v[106:107], v[228:229]
	v_pk_fma_f32 v[230:231], v[164:165], v[104:105], v[230:231]
	v_pk_fma_f32 v[196:197], v[164:165], v[102:103], v[196:197]
	v_pk_fma_f32 v[198:199], v[166:167], v[102:103], v[198:199]
	v_pk_fma_f32 v[186:187], v[166:167], v[100:101], v[186:187]
	v_pk_fma_f32 v[178:179], v[168:169], v[100:101], v[178:179]
	v_pk_fma_f32 v[170:171], v[172:173], v[100:101], v[170:171]
	v_pk_fma_f32 v[162:163], v[174:175], v[100:101], v[162:163]
	v_pk_fma_f32 v[154:155], v[176:177], v[100:101], v[154:155]
	v_pk_fma_f32 v[2:3], v[182:183], v[102:103], v[2:3]
	v_pk_fma_f32 v[242:243], v[150:151], v[108:109], v[242:243]
	v_pk_fma_f32 v[240:241], v[152:153], v[108:109], v[240:241]
	v_pk_fma_f32 v[238:239], v[152:153], v[106:107], v[238:239]
	v_pk_fma_f32 v[236:237], v[156:157], v[106:107], v[236:237]
	v_pk_fma_f32 v[234:235], v[158:159], v[106:107], v[234:235]
	v_pk_fma_f32 v[232:233], v[160:161], v[106:107], v[232:233]
	v_pk_fma_f32 v[228:229], v[166:167], v[108:109], v[228:229]
	v_add_u32_e32 v146, v215, v226
	v_add_u32_e32 v146, 0x2000, v146
	v_ashrrev_i32_e32 v147, 31, v146
	v_lshlrev_b64 v[144:145], 10, v[146:147]
	v_lshl_add_u64 v[144:145], v[86:87], 0, v[144:145]
	global_load_dwordx2 v[128:129], v[144:145], off
	global_load_dwordx2 v[130:131], v[144:145], off offset:512
	global_load_dwordx2 v[132:133], v[144:145], off offset:1024
	global_load_dwordx2 v[134:135], v[144:145], off offset:1536
	global_load_dwordx2 v[136:137], v[144:145], off offset:2048
	global_load_dwordx2 v[138:139], v[144:145], off offset:2560
	global_load_dwordx2 v[140:141], v[144:145], off offset:3072
	global_load_dwordx2 v[142:143], v[144:145], off offset:3584
	v_pk_fma_f32 v[230:231], v[166:167], v[106:107], v[230:231]
	v_pk_fma_f32 v[196:197], v[166:167], v[104:105], v[196:197]
	v_pk_fma_f32 v[198:199], v[168:169], v[104:105], v[198:199]
	v_pk_fma_f32 v[186:187], v[168:169], v[102:103], v[186:187]
	v_pk_fma_f32 v[178:179], v[172:173], v[102:103], v[178:179]
	v_pk_fma_f32 v[170:171], v[174:175], v[102:103], v[170:171]
	v_pk_fma_f32 v[162:163], v[176:177], v[102:103], v[162:163]
	v_pk_fma_f32 v[154:155], v[180:181], v[102:103], v[154:155]
	v_pk_fma_f32 v[2:3], v[184:185], v[104:105], v[2:3]
	v_pk_fma_f32 v[242:243], v[152:153], v[110:111], v[242:243]
	v_pk_fma_f32 v[240:241], v[156:157], v[110:111], v[240:241]
	v_pk_fma_f32 v[238:239], v[156:157], v[108:109], v[238:239]
	v_pk_fma_f32 v[236:237], v[158:159], v[108:109], v[236:237]
	v_pk_fma_f32 v[234:235], v[160:161], v[108:109], v[234:235]
	v_pk_fma_f32 v[232:233], v[164:165], v[108:109], v[232:233]
	v_pk_fma_f32 v[228:229], v[168:169], v[110:111], v[228:229]
	v_pk_fma_f32 v[230:231], v[168:169], v[108:109], v[230:231]
	v_pk_fma_f32 v[196:197], v[168:169], v[106:107], v[196:197]
	v_pk_fma_f32 v[198:199], v[172:173], v[106:107], v[198:199]
	v_pk_fma_f32 v[186:187], v[172:173], v[104:105], v[186:187]
	v_pk_fma_f32 v[178:179], v[174:175], v[104:105], v[178:179]
	v_pk_fma_f32 v[170:171], v[176:177], v[104:105], v[170:171]
	v_pk_fma_f32 v[162:163], v[180:181], v[104:105], v[162:163]
	v_pk_fma_f32 v[154:155], v[182:183], v[104:105], v[154:155]
	v_pk_fma_f32 v[2:3], v[188:189], v[106:107], v[2:3]
	v_pk_fma_f32 v[242:243], v[156:157], v[112:113], v[242:243]
	v_pk_fma_f32 v[240:241], v[158:159], v[112:113], v[240:241]
	v_pk_fma_f32 v[238:239], v[158:159], v[110:111], v[238:239]
	v_pk_fma_f32 v[236:237], v[160:161], v[110:111], v[236:237]
	v_pk_fma_f32 v[234:235], v[164:165], v[110:111], v[234:235]
	v_pk_fma_f32 v[232:233], v[166:167], v[110:111], v[232:233]
	v_pk_fma_f32 v[228:229], v[172:173], v[112:113], v[228:229]
	v_pk_fma_f32 v[230:231], v[172:173], v[110:111], v[230:231]
	v_pk_fma_f32 v[196:197], v[172:173], v[108:109], v[196:197]
	v_pk_fma_f32 v[198:199], v[174:175], v[108:109], v[198:199]
	v_pk_fma_f32 v[186:187], v[174:175], v[106:107], v[186:187]
	v_pk_fma_f32 v[178:179], v[176:177], v[106:107], v[178:179]
	v_pk_fma_f32 v[170:171], v[180:181], v[106:107], v[170:171]
	v_pk_fma_f32 v[162:163], v[182:183], v[106:107], v[162:163]
	v_pk_fma_f32 v[154:155], v[184:185], v[106:107], v[154:155]
	v_pk_fma_f32 v[2:3], v[190:191], v[108:109], v[2:3]
	v_pk_fma_f32 v[242:243], v[158:159], v[114:115], v[242:243]
	v_pk_fma_f32 v[240:241], v[160:161], v[114:115], v[240:241]
	v_pk_fma_f32 v[238:239], v[160:161], v[112:113], v[238:239]
	v_pk_fma_f32 v[236:237], v[164:165], v[112:113], v[236:237]
	v_pk_fma_f32 v[234:235], v[166:167], v[112:113], v[234:235]
	v_pk_fma_f32 v[232:233], v[168:169], v[112:113], v[232:233]
	v_pk_fma_f32 v[228:229], v[174:175], v[114:115], v[228:229]
	v_pk_fma_f32 v[230:231], v[174:175], v[112:113], v[230:231]
	v_pk_fma_f32 v[196:197], v[174:175], v[110:111], v[196:197]
	v_pk_fma_f32 v[198:199], v[176:177], v[110:111], v[198:199]
	v_pk_fma_f32 v[186:187], v[176:177], v[108:109], v[186:187]
	v_pk_fma_f32 v[178:179], v[180:181], v[108:109], v[178:179]
	v_pk_fma_f32 v[170:171], v[182:183], v[108:109], v[170:171]
	v_pk_fma_f32 v[162:163], v[184:185], v[108:109], v[162:163]
	v_pk_fma_f32 v[154:155], v[188:189], v[108:109], v[154:155]
	v_pk_fma_f32 v[2:3], v[192:193], v[110:111], v[2:3]
	v_pk_fma_f32 v[242:243], v[160:161], v[116:117], v[242:243]
	v_pk_fma_f32 v[240:241], v[164:165], v[116:117], v[240:241]
	v_pk_fma_f32 v[238:239], v[164:165], v[114:115], v[238:239]
	v_pk_fma_f32 v[236:237], v[166:167], v[114:115], v[236:237]
	v_pk_fma_f32 v[234:235], v[168:169], v[114:115], v[234:235]
	v_pk_fma_f32 v[232:233], v[172:173], v[114:115], v[232:233]
	v_pk_fma_f32 v[228:229], v[176:177], v[116:117], v[228:229]
	v_pk_fma_f32 v[230:231], v[176:177], v[114:115], v[230:231]
	v_pk_fma_f32 v[196:197], v[176:177], v[112:113], v[196:197]
	v_pk_fma_f32 v[198:199], v[180:181], v[112:113], v[198:199]
	v_pk_fma_f32 v[186:187], v[180:181], v[110:111], v[186:187]
	v_pk_fma_f32 v[178:179], v[182:183], v[110:111], v[178:179]
	v_pk_fma_f32 v[170:171], v[184:185], v[110:111], v[170:171]
	v_pk_fma_f32 v[162:163], v[188:189], v[110:111], v[162:163]
	v_pk_fma_f32 v[154:155], v[190:191], v[110:111], v[154:155]
	v_pk_fma_f32 v[2:3], v[194:195], v[112:113], v[2:3]
	v_pk_fma_f32 v[242:243], v[164:165], v[118:119], v[242:243]
	v_pk_fma_f32 v[240:241], v[166:167], v[118:119], v[240:241]
	v_pk_fma_f32 v[238:239], v[166:167], v[116:117], v[238:239]
	v_pk_fma_f32 v[236:237], v[168:169], v[116:117], v[236:237]
	v_pk_fma_f32 v[234:235], v[172:173], v[116:117], v[234:235]
	v_pk_fma_f32 v[232:233], v[174:175], v[116:117], v[232:233]
	v_pk_fma_f32 v[228:229], v[180:181], v[118:119], v[228:229]
	v_pk_fma_f32 v[230:231], v[180:181], v[116:117], v[230:231]
	v_pk_fma_f32 v[196:197], v[180:181], v[114:115], v[196:197]
	v_pk_fma_f32 v[198:199], v[182:183], v[114:115], v[198:199]
	v_pk_fma_f32 v[186:187], v[182:183], v[112:113], v[186:187]
	v_pk_fma_f32 v[178:179], v[184:185], v[112:113], v[178:179]
	v_pk_fma_f32 v[170:171], v[188:189], v[112:113], v[170:171]
	v_pk_fma_f32 v[162:163], v[190:191], v[112:113], v[162:163]
	v_pk_fma_f32 v[154:155], v[192:193], v[112:113], v[154:155]
	v_pk_fma_f32 v[2:3], v[200:201], v[114:115], v[2:3]
	v_pk_fma_f32 v[242:243], v[166:167], v[120:121], v[242:243]
	v_pk_fma_f32 v[240:241], v[168:169], v[120:121], v[240:241]
	v_pk_fma_f32 v[238:239], v[168:169], v[118:119], v[238:239]
	v_pk_fma_f32 v[236:237], v[172:173], v[118:119], v[236:237]
	v_pk_fma_f32 v[234:235], v[174:175], v[118:119], v[234:235]
	v_pk_fma_f32 v[232:233], v[176:177], v[118:119], v[232:233]
	v_pk_fma_f32 v[228:229], v[182:183], v[120:121], v[228:229]
	v_pk_fma_f32 v[230:231], v[182:183], v[118:119], v[230:231]
	v_pk_fma_f32 v[196:197], v[182:183], v[116:117], v[196:197]
	v_pk_fma_f32 v[198:199], v[184:185], v[116:117], v[198:199]
	v_pk_fma_f32 v[186:187], v[184:185], v[114:115], v[186:187]
	v_pk_fma_f32 v[178:179], v[188:189], v[114:115], v[178:179]
	v_pk_fma_f32 v[170:171], v[190:191], v[114:115], v[170:171]
	v_pk_fma_f32 v[162:163], v[192:193], v[114:115], v[162:163]
	v_pk_fma_f32 v[154:155], v[194:195], v[114:115], v[154:155]
	v_pk_fma_f32 v[2:3], v[202:203], v[116:117], v[2:3]
	v_pk_fma_f32 v[242:243], v[168:169], v[122:123], v[242:243]
	v_pk_fma_f32 v[240:241], v[172:173], v[122:123], v[240:241]
	v_pk_fma_f32 v[238:239], v[172:173], v[120:121], v[238:239]
	v_pk_fma_f32 v[236:237], v[174:175], v[120:121], v[236:237]
	v_pk_fma_f32 v[234:235], v[176:177], v[120:121], v[234:235]
	v_pk_fma_f32 v[232:233], v[180:181], v[120:121], v[232:233]
	v_pk_fma_f32 v[228:229], v[184:185], v[122:123], v[228:229]
	v_pk_fma_f32 v[230:231], v[184:185], v[120:121], v[230:231]
	v_pk_fma_f32 v[196:197], v[184:185], v[118:119], v[196:197]
	v_pk_fma_f32 v[198:199], v[188:189], v[118:119], v[198:199]
	v_pk_fma_f32 v[186:187], v[188:189], v[116:117], v[186:187]
	v_pk_fma_f32 v[178:179], v[190:191], v[116:117], v[178:179]
	v_lshlrev_b32_e32 v206, 16, v207
	v_and_b32_e32 v207, 0xffff0000, v207
	v_pk_fma_f32 v[170:171], v[192:193], v[116:117], v[170:171]
	v_pk_fma_f32 v[162:163], v[194:195], v[116:117], v[162:163]
	v_pk_fma_f32 v[154:155], v[200:201], v[116:117], v[154:155]
	v_pk_fma_f32 v[2:3], v[204:205], v[118:119], v[2:3]
	v_pk_fma_f32 v[242:243], v[172:173], v[124:125], v[242:243]
	v_pk_fma_f32 v[240:241], v[174:175], v[124:125], v[240:241]
	v_pk_fma_f32 v[238:239], v[174:175], v[122:123], v[238:239]
	v_pk_fma_f32 v[236:237], v[176:177], v[122:123], v[236:237]
	v_pk_fma_f32 v[234:235], v[180:181], v[122:123], v[234:235]
	v_pk_fma_f32 v[232:233], v[182:183], v[122:123], v[232:233]
	v_pk_fma_f32 v[228:229], v[188:189], v[124:125], v[228:229]
	v_pk_fma_f32 v[230:231], v[188:189], v[122:123], v[230:231]
	v_pk_fma_f32 v[196:197], v[188:189], v[120:121], v[196:197]
	v_pk_fma_f32 v[198:199], v[190:191], v[120:121], v[198:199]
	v_pk_fma_f32 v[186:187], v[190:191], v[118:119], v[186:187]
	v_pk_fma_f32 v[178:179], v[192:193], v[118:119], v[178:179]
	v_pk_fma_f32 v[170:171], v[194:195], v[118:119], v[170:171]
	v_lshlrev_b32_e32 v208, 16, v209
	v_and_b32_e32 v209, 0xffff0000, v209
	v_pk_fma_f32 v[162:163], v[200:201], v[118:119], v[162:163]
	v_pk_fma_f32 v[154:155], v[202:203], v[118:119], v[154:155]
	v_pk_fma_f32 v[2:3], v[206:207], v[120:121], v[2:3]
	v_pk_fma_f32 v[242:243], v[174:175], v[126:127], v[242:243]
	v_pk_fma_f32 v[240:241], v[176:177], v[126:127], v[240:241]
	v_pk_fma_f32 v[238:239], v[176:177], v[124:125], v[238:239]
	v_pk_fma_f32 v[236:237], v[180:181], v[124:125], v[236:237]
	v_pk_fma_f32 v[234:235], v[182:183], v[124:125], v[234:235]
	v_pk_fma_f32 v[232:233], v[184:185], v[124:125], v[232:233]
	v_pk_fma_f32 v[228:229], v[190:191], v[126:127], v[228:229]
	v_pk_fma_f32 v[230:231], v[190:191], v[124:125], v[230:231]
	v_pk_fma_f32 v[196:197], v[190:191], v[122:123], v[196:197]
	v_pk_fma_f32 v[198:199], v[192:193], v[122:123], v[198:199]
	v_pk_fma_f32 v[186:187], v[192:193], v[120:121], v[186:187]
	v_pk_fma_f32 v[178:179], v[194:195], v[120:121], v[178:179]
	v_pk_fma_f32 v[170:171], v[200:201], v[120:121], v[170:171]
	v_pk_fma_f32 v[162:163], v[202:203], v[120:121], v[162:163]
	v_lshlrev_b32_e32 v210, 16, v211
	v_and_b32_e32 v211, 0xffff0000, v211
	v_pk_fma_f32 v[154:155], v[204:205], v[120:121], v[154:155]
	v_pk_fma_f32 v[2:3], v[208:209], v[122:123], v[2:3]
	v_add_u32_e32 v120, v215, v226
	v_pk_fma_f32 v[238:239], v[180:181], v[126:127], v[238:239]
	v_pk_fma_f32 v[236:237], v[182:183], v[126:127], v[236:237]
	v_pk_fma_f32 v[234:235], v[184:185], v[126:127], v[234:235]
	v_pk_fma_f32 v[232:233], v[188:189], v[126:127], v[232:233]
	v_pk_fma_f32 v[230:231], v[192:193], v[126:127], v[230:231]
	ds_write2st64_b64 v214, v[242:243], v[240:241] offset1:4
	ds_write2st64_b64 v214, v[238:239], v[236:237] offset0:8 offset1:12
	ds_write2st64_b64 v214, v[234:235], v[232:233] offset0:16 offset1:20
	ds_write2st64_b64 v214, v[228:229], v[230:231] offset0:24 offset1:28
	v_pk_fma_f32 v[196:197], v[192:193], v[124:125], v[196:197]
	v_pk_fma_f32 v[198:199], v[194:195], v[124:125], v[198:199]
	v_pk_fma_f32 v[186:187], v[194:195], v[122:123], v[186:187]
	v_pk_fma_f32 v[178:179], v[200:201], v[122:123], v[178:179]
	v_pk_fma_f32 v[170:171], v[202:203], v[122:123], v[170:171]
	v_pk_fma_f32 v[162:163], v[204:205], v[122:123], v[162:163]
	v_pk_fma_f32 v[154:155], v[206:207], v[122:123], v[154:155]
	v_lshlrev_b32_e32 v228, 16, v227
	v_and_b32_e32 v229, 0xffff0000, v227
	v_pk_fma_f32 v[2:3], v[210:211], v[124:125], v[2:3]
	v_add_u32_e32 v98, 0x2000, v120
	v_pk_fma_f32 v[196:197], v[194:195], v[126:127], v[196:197]
	v_pk_fma_f32 v[198:199], v[200:201], v[126:127], v[198:199]
	v_pk_fma_f32 v[186:187], v[200:201], v[124:125], v[186:187]
	v_pk_fma_f32 v[178:179], v[202:203], v[124:125], v[178:179]
	v_pk_fma_f32 v[170:171], v[204:205], v[124:125], v[170:171]
	v_pk_fma_f32 v[162:163], v[206:207], v[124:125], v[162:163]
	v_pk_fma_f32 v[154:155], v[208:209], v[124:125], v[154:155]
	v_pk_fma_f32 v[2:3], v[228:229], v[126:127], v[2:3]
	v_ashrrev_i32_e32 v99, 31, v98
	v_pk_fma_f32 v[186:187], v[202:203], v[126:127], v[186:187]
	v_pk_fma_f32 v[178:179], v[204:205], v[126:127], v[178:179]
	v_pk_fma_f32 v[170:171], v[206:207], v[126:127], v[170:171]
	v_pk_fma_f32 v[162:163], v[208:209], v[126:127], v[162:163]
	v_pk_fma_f32 v[154:155], v[210:211], v[126:127], v[154:155]
	ds_write2st64_b64 v214, v[196:197], v[198:199] offset0:32 offset1:36
	ds_write2st64_b64 v214, v[186:187], v[178:179] offset0:40 offset1:44
	ds_write2st64_b64 v214, v[170:171], v[162:163] offset0:48 offset1:52
	ds_write2st64_b64 v214, v[154:155], v[2:3] offset0:56 offset1:60
	v_lshlrev_b64 v[2:3], 10, v[98:99]
	v_lshl_add_u64 v[2:3], v[86:87], 0, v[2:3]
	s_waitcnt lgkmcnt(0)
	s_barrier
	v_add_u32_e32 v226, s9, v226
	s_waitcnt vmcnt(7)
	v_lshlrev_b32_e32 v100, 16, v128
	v_and_b32_e32 v101, 0xffff0000, v128
	v_lshlrev_b32_e32 v102, 16, v129
	v_and_b32_e32 v103, 0xffff0000, v129
	s_waitcnt vmcnt(6)
	v_lshlrev_b32_e32 v104, 16, v130
	v_and_b32_e32 v105, 0xffff0000, v130
	v_lshlrev_b32_e32 v106, 16, v131
	v_and_b32_e32 v107, 0xffff0000, v131
	global_load_dwordx4 v[2:5], v[82:83], off offset:1024
	global_load_dwordx4 v[6:9], v[84:85], off offset:1024
	ds_read_b128 v[90:93], v216 offset:1024
	global_load_dwordx4 v[10:13], v[82:83], off
	global_load_dwordx4 v[14:17], v[84:85], off
	ds_read_b128 v[94:97], v216
	s_waitcnt lgkmcnt(1)
	v_pk_mul_f32 v[110:111], v[90:91], v[90:91]
	v_pk_mul_f32 v[108:109], v[92:93], v[92:93]
	s_waitcnt lgkmcnt(0)
	v_mov_b32_e32 v114, v94
	v_mov_b32_e32 v115, v96
	v_pk_mul_f32 v[114:115], v[114:115], v[114:115]
	v_pk_mul_f32 v[116:117], v[94:95], v[94:95]
	v_mov_b32_e32 v118, v114
	v_mov_b32_e32 v119, v94
	v_mov_b32_e32 v116, v117
	v_mov_b32_e32 v117, v95
	v_pk_mul_f32 v[112:113], v[96:97], v[96:97]
	v_pk_add_f32 v[116:117], v[118:119], v[116:117]
	v_pk_mov_b32 v[114:115], v[114:115], v[96:97] op_sel:[1,0]
	v_mov_b32_e32 v112, v113
	v_pk_add_f32 v[114:115], v[116:117], v[114:115]
	v_mov_b32_e32 v113, v97
	v_pk_add_f32 v[112:113], v[114:115], v[112:113]
	v_mov_b32_e32 v114, v110
	v_mov_b32_e32 v115, v90
	v_pk_add_f32 v[112:113], v[112:113], v[114:115]
	v_mov_b32_e32 v110, v111
	v_mov_b32_e32 v111, v91
	v_pk_add_f32 v[110:111], v[112:113], v[110:111]
	v_mov_b32_e32 v112, v108
	v_mov_b32_e32 v113, v92
	v_pk_add_f32 v[110:111], v[110:111], v[112:113]
	v_mov_b32_e32 v108, v109
	v_mov_b32_e32 v109, v93
	v_pk_add_f32 v[108:109], v[110:111], v[108:109]
	ds_bpermute_b32 v111, v217, v109
	ds_bpermute_b32 v110, v217, v108
	s_waitcnt lgkmcnt(0)
	v_pk_add_f32 v[108:109], v[108:109], v[110:111]
	ds_bpermute_b32 v111, v218, v109
	ds_bpermute_b32 v110, v218, v108
	s_waitcnt lgkmcnt(0)
	v_pk_add_f32 v[108:109], v[108:109], v[110:111]
	ds_bpermute_b32 v111, v219, v109
	ds_bpermute_b32 v110, v219, v108
	s_waitcnt lgkmcnt(0)
	v_pk_add_f32 v[108:109], v[108:109], v[110:111]
	ds_bpermute_b32 v111, v220, v109
	ds_bpermute_b32 v110, v220, v108
	s_waitcnt lgkmcnt(0)
	v_pk_add_f32 v[108:109], v[108:109], v[110:111]
	ds_bpermute_b32 v111, v221, v109
	ds_bpermute_b32 v110, v221, v108
	s_waitcnt lgkmcnt(0)
	v_pk_add_f32 v[108:109], v[108:109], v[110:111]
	ds_bpermute_b32 v111, v222, v109
	ds_bpermute_b32 v110, v222, v108
	s_waitcnt lgkmcnt(0)
	v_pk_add_f32 v[108:109], v[108:109], v[110:111]
	s_nop 0
	v_pk_mul_f32 v[108:109], v[108:109], s[6:7] op_sel_hi:[1,0]
	s_nop 0
	v_fma_f32 v110, -v109, v109, v108
	v_max_f32_e32 v110, 0, v110
	v_add_f32_e32 v110, 0x358637bd, v110
	v_cmp_gt_f32_e32 vcc, s22, v110
	v_mul_f32_e32 v111, 0x4b800000, v110
	v_pk_add_f32 v[94:95], v[94:95], v[108:109] op_sel:[0,1] neg_lo:[0,1] neg_hi:[0,1]
	v_cndmask_b32_e32 v110, v110, v111, vcc
	v_rsq_f32_e32 v110, v110
	v_pk_add_f32 v[96:97], v[96:97], v[108:109] op_sel:[0,1] neg_lo:[0,1] neg_hi:[0,1]
	v_pk_add_f32 v[90:91], v[90:91], v[108:109] op_sel:[0,1] neg_lo:[0,1] neg_hi:[0,1]
	v_pk_add_f32 v[92:93], v[92:93], v[108:109] op_sel:[0,1] neg_lo:[0,1] neg_hi:[0,1]
	v_mul_f32_e32 v111, 0x45800000, v110
	v_cndmask_b32_e32 v110, v110, v111, vcc
	v_pk_mul_f32 v[94:95], v[94:95], v[110:111] op_sel_hi:[1,0]
	s_waitcnt vmcnt(0)
	v_cmp_ge_i32_e64 s[98:99], s23, v1
	s_nop 0
	s_and_b64 s[98:99], s[98:99], exec
	s_cbranch_scc0 .Lcpf_skip_nxt
	v_lshrrev_b32_e32 v253, 12, v226
	v_cmp_gt_i32_e64 s[98:99], s10, v1
	v_lshrrev_b32_e32 v252, 4, v1
	v_add_u32_e32 v253, 32, v253
	v_cndmask_b32_e64 v252, v253, v252, s[98:99]
	v_lshlrev_b32_e32 v252, 5, v252
	v_add3_u32 v252, v226, v252, s11
	v_ashrrev_i32_e32 v253, 31, v252
	v_lshlrev_b64 v[252:253], 10, v[252:253]
	v_lshl_add_u64 v[252:253], v[78:79], 0, v[252:253]
	s_mov_b64 s[100:101], 0x1000
	v_lshl_add_u64 v[252:253], v[252:253], 0, s[100:101]
	s_mov_b64 s[100:101], 0x2000
	global_load_dword v146, v[252:253], off offset:-4096
	global_load_dword v145, v[252:253], off offset:-3072
	global_load_dword v150, v[252:253], off offset:-2048
	global_load_dword v152, v[252:253], off offset:-1024
	global_load_dword v156, v[252:253], off
	global_load_dword v158, v[252:253], off offset:1024
	global_load_dword v160, v[252:253], off offset:2048
	global_load_dword v164, v[252:253], off offset:3072
	v_lshl_add_u64 v[252:253], v[252:253], 0, s[100:101]
	global_load_dword v166, v[252:253], off offset:-4096
	global_load_dword v168, v[252:253], off offset:-3072
	global_load_dword v172, v[252:253], off offset:-2048
	global_load_dword v174, v[252:253], off offset:-1024
	global_load_dword v176, v[252:253], off
	global_load_dword v144, v[252:253], off offset:1024
	global_load_dword v251, v[252:253], off offset:2048
	global_load_dword v250, v[252:253], off offset:3072
	v_lshl_add_u64 v[252:253], v[252:253], 0, s[100:101]
	global_load_dword v249, v[252:253], off offset:-4096
	global_load_dword v248, v[252:253], off offset:-3072
	global_load_dword v246, v[252:253], off offset:-2048
	global_load_dword v247, v[252:253], off offset:-1024
	global_load_dword v147, v[252:253], off
	global_load_dword v151, v[252:253], off offset:1024
	global_load_dword v153, v[252:253], off offset:2048
	global_load_dword v157, v[252:253], off offset:3072
	v_lshl_add_u64 v[252:253], v[252:253], 0, s[100:101]
	global_load_dword v159, v[252:253], off offset:-4096
	global_load_dword v161, v[252:253], off offset:-3072
	global_load_dword v165, v[252:253], off offset:-2048
	global_load_dword v167, v[252:253], off offset:-1024
	global_load_dword v169, v[252:253], off
	global_load_dword v173, v[252:253], off offset:1024
	global_load_dword v175, v[252:253], off offset:2048
	global_load_dword v177, v[252:253], off offset:3072
	v_lshl_add_u64 v[252:253], v[252:253], 0, s[100:101]
	global_load_dword v181, v[252:253], off offset:-4096
	global_load_dword v183, v[252:253], off offset:-3072
	global_load_dword v185, v[252:253], off offset:-2048
	global_load_dword v189, v[252:253], off offset:-1024
	global_load_dword v191, v[252:253], off
	global_load_dword v193, v[252:253], off offset:1024
	global_load_dword v195, v[252:253], off offset:2048
	global_load_dword v201, v[252:253], off offset:3072
	v_lshl_add_u64 v[252:253], v[252:253], 0, s[100:101]
	global_load_dword v203, v[252:253], off offset:-4096
	global_load_dword v205, v[252:253], off offset:-3072
	global_load_dword v207, v[252:253], off offset:-2048
	global_load_dword v209, v[252:253], off offset:-1024
	global_load_dword v211, v[252:253], off
	global_load_dword v227, v[252:253], off offset:1024
